# G9 layer-0 tail round split 4-way along K (write-through partials, counter + fences, fixed-order combine) with the wave-group barrier stagger re-aligned around the publish; G8 left unsplit
# speedup vs baseline: 1.0161x; 1.0026x over previous
; #define PG8_STAGE(bufoff, gbase, voff) do { _Pragma("unroll") for (int _i = 0; _i < 2; ++_i) \
;         __builtin_amdgcn_global_load_lds((const unsigned*)((const char*)(gbase) + (voff)[_i]), (LAS unsigned*)(lds + (bufoff) + ldsw + _i * 8192), 16, 0, 0); } while (0)
; #define PG8_LDA(dst, b, h) do { _Pragma("unroll") for (int m = 0; m < 4; ++m) _Pragma("unroll") for (int k = 0; k < 2; ++k) dst[m][k] = *(const LAS bf16x8*)(lds + PG8_SA(b, h) + aoff + m * 2048 + k * 1024); } while (0)
; #define PG8_LDB(dst, b, h) do { _Pragma("unroll") for (int n = 0; n < 2; ++n) _Pragma("unroll") for (int k = 0; k < 2; ++k) dst[n][k] = *(const LAS bf16x8*)(lds + PG8_SB(b, h) + boff + n * 2048 + k * 1024); } while (0)
; #define PG8_MMA(ai, bj, At, Bt) do { __builtin_amdgcn_s_setprio(1); _Pragma("unroll") for (int m = 0; m < 4; ++m) _Pragma("unroll") for (int n = 0; n < 2; ++n) _Pragma("unroll") for (int k = 0; k < 2; ++k) \
;         acc[ai][bj][m][n] = __builtin_amdgcn_mfma_f32_16x16x32_bf16(Bt[n][k], At[m][k], acc[ai][bj][m][n], 0, 0, 0); __builtin_amdgcn_s_setprio(0); } while (0)
; #define PG8_WAIT_L(n) asm volatile("s_waitcnt lgkmcnt(" #n ")" ::: "memory")
; #define PG8_BAR __builtin_amdgcn_s_barrier()
; #define PG8_SCHED __builtin_amdgcn_sched_barrier(0)
; template <class Epi, class SchedT>
; DI void gemm_phase(LAS unsigned char* lds, const Gemm g, const SchedT& S, const Epi& E) {
;     ...
;             PG8_LDB(B0, 0, 0); PG8_SCHED; PG8_LDA(At, 0, 0); PG8_STAGE(PG8_SA(1, 1), a1 + hstepA, voffA);
;             PG8_WAIT_L(8); PG8_BAR; PG8_WAIT_L(0); PG8_MMA(0, 0, At, B0); PG8_BAR; PG8_SCHED;
;             PG8_LDB(B1, 0, 1); PG8_STAGE(PG8_SB(0, 0), b2, voffB);
;             PG8_BAR; PG8_WAIT_L(0); PG8_MMA(0, 1, At, B1); PG8_BAR;
;             PG8_LDA(At, 0, 1); PG8_STAGE(PG8_SA(0, 0), a2, voffA);
;             PG8_BAR; PG8_WAIT_L(0); PG8_MMA(1, 0, At, B0); PG8_BAR; PG8_SCHED;
.LBB0_1705:
	s_add_u32 s10, s8, 0xffea0080
	s_addc_u32 s11, s9, -1
	s_add_i32 s42, 0, 0x10000
	v_add_u32_e32 v36, s42, v150
	ds_read_b128 v[46:49], v36
	ds_read_b128 v[54:57], v36 offset:1024
	ds_read_b128 v[62:65], v36 offset:2048
	ds_read_b128 v[152:155], v36 offset:3072
	s_cmpk_eq_i32 s41, 0x54
	s_cselect_b32 s13, s7, s11
	s_cselect_b32 s12, s6, s10
	s_cselect_b32 s11, s1, s40
	s_cselect_b32 s10, s0, s39
	v_lshl_add_u64 v[36:37], s[8:9], 0, v[0:1]
	s_add_i32 m0, s24, 0xc000
	ds_read_b128 v[156:159], v151
	ds_read_b128 v[160:163], v151 offset:1024
	ds_read_b128 v[164:167], v151 offset:2048
	ds_read_b128 v[168:171], v151 offset:3072
	ds_read_b128 v[172:175], v151 offset:4096
	ds_read_b128 v[176:179], v151 offset:5120
	ds_read_b128 v[184:187], v151 offset:6144
	ds_read_b128 v[188:191], v151 offset:7168
	global_load_lds_dwordx4 v[36:37], off
	v_lshl_add_u64 v[36:37], s[8:9], 0, v[34:35]
	s_add_i32 m0, s24, 0xe000
	s_nop 0
	global_load_lds_dwordx4 v[36:37], off
	s_waitcnt lgkmcnt(8)
	s_barrier
	s_waitcnt lgkmcnt(0)
	s_setprio 1
	s_waitcnt lgkmcnt(0)
	v_mfma_f32_16x16x32_bf16 v[142:145], v[46:49], v[156:159], v[142:145]
	v_mfma_f32_16x16x32_bf16 v[138:141], v[62:65], v[156:159], v[138:141]
	v_mfma_f32_16x16x32_bf16 v[126:129], v[46:49], v[164:167], v[126:129]
	v_mfma_f32_16x16x32_bf16 v[122:125], v[62:65], v[164:167], v[122:125]
	v_mfma_f32_16x16x32_bf16 v[110:113], v[46:49], v[172:175], v[110:113]
	v_mfma_f32_16x16x32_bf16 v[106:109], v[62:65], v[172:175], v[106:109]
	v_mfma_f32_16x16x32_bf16 v[94:97], v[46:49], v[184:187], v[94:97]
	v_mfma_f32_16x16x32_bf16 v[90:93], v[62:65], v[184:187], v[90:93]
	v_mfma_f32_16x16x32_bf16 v[142:145], v[54:57], v[160:163], v[142:145]
	v_mfma_f32_16x16x32_bf16 v[138:141], v[152:155], v[160:163], v[138:141]
	v_mfma_f32_16x16x32_bf16 v[126:129], v[54:57], v[168:171], v[126:129]
	v_mfma_f32_16x16x32_bf16 v[122:125], v[152:155], v[168:171], v[122:125]
	v_mfma_f32_16x16x32_bf16 v[110:113], v[54:57], v[176:179], v[110:113]
	v_mfma_f32_16x16x32_bf16 v[106:109], v[152:155], v[176:179], v[106:109]
	v_mfma_f32_16x16x32_bf16 v[94:97], v[54:57], v[188:191], v[94:97]
	v_mfma_f32_16x16x32_bf16 v[90:93], v[152:155], v[188:191], v[90:93]
	s_setprio 0
	s_barrier
	s_add_i32 s44, 0, 0x14000
	s_add_i32 s42, s42, s18
	v_add_u32_e32 v36, s44, v150
	v_lshl_add_u64 v[146:147], s[10:11], 0, v[0:1]
	s_mov_b32 m0, s42
	ds_read_b128 v[202:205], v36
	ds_read_b128 v[206:209], v36 offset:1024
	ds_read_b128 v[210:213], v36 offset:2048
	ds_read_b128 v[214:217], v36 offset:3072
	global_load_lds_dwordx4 v[146:147], off
	v_lshl_add_u64 v[180:181], s[10:11], 0, v[34:35]
	s_add_i32 m0, s42, 0x2000
	s_nop 0
	global_load_lds_dwordx4 v[180:181], off
	s_barrier
	s_waitcnt lgkmcnt(0)
	s_setprio 1
	s_waitcnt lgkmcnt(0)
	v_mfma_f32_16x16x32_bf16 v[134:137], v[202:205], v[156:159], v[134:137]
	v_mfma_f32_16x16x32_bf16 v[130:133], v[210:213], v[156:159], v[130:133]
	v_mfma_f32_16x16x32_bf16 v[118:121], v[202:205], v[164:167], v[118:121]
	v_mfma_f32_16x16x32_bf16 v[114:117], v[210:213], v[164:167], v[114:117]
	v_mfma_f32_16x16x32_bf16 v[102:105], v[202:205], v[172:175], v[102:105]
	v_mfma_f32_16x16x32_bf16 v[98:101], v[210:213], v[172:175], v[98:101]
	v_mfma_f32_16x16x32_bf16 v[86:89], v[202:205], v[184:187], v[86:89]
	v_mfma_f32_16x16x32_bf16 v[82:85], v[210:213], v[184:187], v[82:85]
	v_mfma_f32_16x16x32_bf16 v[134:137], v[206:209], v[160:163], v[134:137]
	v_mfma_f32_16x16x32_bf16 v[130:133], v[214:217], v[160:163], v[130:133]
	v_mfma_f32_16x16x32_bf16 v[118:121], v[206:209], v[168:171], v[118:121]
	v_mfma_f32_16x16x32_bf16 v[114:117], v[214:217], v[168:171], v[114:117]
	v_mfma_f32_16x16x32_bf16 v[102:105], v[206:209], v[176:179], v[102:105]
	v_mfma_f32_16x16x32_bf16 v[98:101], v[214:217], v[176:179], v[98:101]
	v_mfma_f32_16x16x32_bf16 v[86:89], v[206:209], v[188:191], v[86:89]
	v_mfma_f32_16x16x32_bf16 v[82:85], v[214:217], v[188:191], v[82:85]
	s_setprio 0
	s_mov_b32 m0, s24
	v_lshl_add_u64 v[182:183], s[12:13], 0, v[0:1]
	s_barrier
	ds_read_b128 v[156:159], v151 offset:16384
	ds_read_b128 v[160:163], v151 offset:17408
	ds_read_b128 v[164:167], v151 offset:18432
	ds_read_b128 v[168:171], v151 offset:19456
	ds_read_b128 v[172:175], v151 offset:20480
	ds_read_b128 v[176:179], v151 offset:21504
	ds_read_b128 v[184:187], v151 offset:22528
	ds_read_b128 v[188:191], v151 offset:23552
	global_load_lds_dwordx4 v[182:183], off
	v_lshl_add_u64 v[194:195], s[12:13], 0, v[34:35]
	s_mov_b32 m0, s25
	s_nop 0
	global_load_lds_dwordx4 v[194:195], off
	s_barrier
	s_waitcnt lgkmcnt(0)
	s_setprio 1
	s_waitcnt lgkmcnt(0)
	v_mfma_f32_16x16x32_bf16 v[78:81], v[46:49], v[156:159], v[78:81]
	v_mfma_f32_16x16x32_bf16 v[74:77], v[62:65], v[156:159], v[74:77]
	v_mfma_f32_16x16x32_bf16 v[58:61], v[46:49], v[164:167], v[58:61]
	v_mfma_f32_16x16x32_bf16 v[50:53], v[62:65], v[164:167], v[50:53]
	v_mfma_f32_16x16x32_bf16 v[30:33], v[46:49], v[172:175], v[30:33]
	v_mfma_f32_16x16x32_bf16 v[26:29], v[62:65], v[172:175], v[26:29]
	v_mfma_f32_16x16x32_bf16 v[14:17], v[46:49], v[184:187], v[14:17]
	v_mfma_f32_16x16x32_bf16 v[10:13], v[62:65], v[184:187], v[10:13]
	v_mfma_f32_16x16x32_bf16 v[78:81], v[54:57], v[160:163], v[78:81]
	v_mfma_f32_16x16x32_bf16 v[74:77], v[152:155], v[160:163], v[74:77]
	v_mfma_f32_16x16x32_bf16 v[58:61], v[54:57], v[168:171], v[58:61]
	v_mfma_f32_16x16x32_bf16 v[50:53], v[152:155], v[168:171], v[50:53]
	v_mfma_f32_16x16x32_bf16 v[30:33], v[54:57], v[176:179], v[30:33]
	v_mfma_f32_16x16x32_bf16 v[26:29], v[152:155], v[176:179], v[26:29]
	v_mfma_f32_16x16x32_bf16 v[14:17], v[54:57], v[188:191], v[14:17]
	v_mfma_f32_16x16x32_bf16 v[10:13], v[152:155], v[188:191], v[10:13]
	s_setprio 0
	s_barrier
; #define PG8_STAGE(bufoff, gbase, voff) do { _Pragma("unroll") for (int _i = 0; _i < 2; ++_i) \
;         __builtin_amdgcn_global_load_lds((const unsigned*)((const char*)(gbase) + (voff)[_i]), (LAS unsigned*)(lds + (bufoff) + ldsw + _i * 8192), 16, 0, 0); } while (0)
; #define PG8_LDA(dst, b, h) do { _Pragma("unroll") for (int m = 0; m < 4; ++m) _Pragma("unroll") for (int k = 0; k < 2; ++k) dst[m][k] = *(const LAS bf16x8*)(lds + PG8_SA(b, h) + aoff + m * 2048 + k * 1024); } while (0)
; #define PG8_LDB(dst, b, h) do { _Pragma("unroll") for (int n = 0; n < 2; ++n) _Pragma("unroll") for (int k = 0; k < 2; ++k) dst[n][k] = *(const LAS bf16x8*)(lds + PG8_SB(b, h) + boff + n * 2048 + k * 1024); } while (0)
; #define PG8_MMA(ai, bj, At, Bt) do { __builtin_amdgcn_s_setprio(1); _Pragma("unroll") for (int m = 0; m < 4; ++m) _Pragma("unroll") for (int n = 0; n < 2; ++n) _Pragma("unroll") for (int k = 0; k < 2; ++k) \
;         acc[ai][bj][m][n] = __builtin_amdgcn_mfma_f32_16x16x32_bf16(Bt[n][k], At[m][k], acc[ai][bj][m][n], 0, 0, 0); __builtin_amdgcn_s_setprio(0); } while (0)
; #define PG8_WAIT_V(n) asm volatile("s_waitcnt vmcnt(" #n ")" ::: "memory")
; #define PG8_WAIT_L(n) asm volatile("s_waitcnt lgkmcnt(" #n ")" ::: "memory")
; #define PG8_BAR __builtin_amdgcn_s_barrier()
; #define PG8_SCHED __builtin_amdgcn_sched_barrier(0)
; template <class Epi, class SchedT>
; DI void gemm_phase(LAS unsigned char* lds, const Gemm g, const SchedT& S, const Epi& E) {
;     ...
;             PG8_STAGE(PG8_SB(0, 1), b2 + hstepB, voffB);
;             PG8_WAIT_V(6); PG8_BAR; PG8_MMA(1, 1, At, B1); PG8_BAR;
;             PG8_LDB(B0, 1, 0); PG8_SCHED; PG8_LDA(At, 1, 0); PG8_STAGE(PG8_SA(0, 1), a2 + hstepA, voffA);
;             PG8_WAIT_L(8); PG8_BAR; PG8_WAIT_L(0); PG8_MMA(0, 0, At, B0); PG8_BAR; PG8_SCHED;
;             PG8_LDB(B1, 1, 1); PG8_STAGE(PG8_SB(1, 0), b3, voffB);
;             PG8_BAR; PG8_WAIT_L(0); PG8_MMA(0, 1, At, B1); PG8_BAR;
;             PG8_LDA(At, 1, 1); PG8_STAGE(PG8_SA(1, 0), a3, voffA);
;             PG8_BAR; PG8_WAIT_L(0); PG8_MMA(1, 0, At, B0); PG8_BAR; PG8_SCHED;
	s_add_u32 s42, s10, 0x160000
	s_addc_u32 s43, s11, 0
	s_add_i32 s44, s44, s18
	v_lshl_add_u64 v[36:37], s[42:43], 0, v[0:1]
	s_mov_b32 m0, s44
	s_nop 0
	global_load_lds_dwordx4 v[36:37], off
	v_lshl_add_u64 v[36:37], s[42:43], 0, v[34:35]
	s_add_i32 m0, s44, 0x2000
	s_nop 0
	global_load_lds_dwordx4 v[36:37], off
	s_waitcnt vmcnt(6)
	s_barrier
	s_setprio 1
	v_mfma_f32_16x16x32_bf16 v[42:45], v[202:205], v[164:167], v[42:45]
	v_mfma_f32_16x16x32_bf16 v[36:39], v[210:213], v[164:167], v[38:41]
	v_mfma_f32_16x16x32_bf16 v[22:25], v[202:205], v[172:175], v[22:25]
	v_mfma_f32_16x16x32_bf16 v[18:21], v[210:213], v[172:175], v[18:21]
	v_mfma_f32_16x16x32_bf16 v[6:9], v[202:205], v[184:187], v[6:9]
	v_mfma_f32_16x16x32_bf16 v[2:5], v[210:213], v[184:187], v[2:5]
	v_mfma_f32_16x16x32_bf16 v[46:49], v[202:205], v[156:159], v[70:73]
	v_mfma_f32_16x16x32_bf16 v[54:57], v[210:213], v[156:159], v[66:69]
	v_mfma_f32_16x16x32_bf16 v[42:45], v[206:209], v[168:171], v[42:45]
	v_mfma_f32_16x16x32_bf16 v[36:39], v[214:217], v[168:171], v[36:39]
	v_mfma_f32_16x16x32_bf16 v[22:25], v[206:209], v[176:179], v[22:25]
	v_mfma_f32_16x16x32_bf16 v[18:21], v[214:217], v[176:179], v[18:21]
	v_mfma_f32_16x16x32_bf16 v[6:9], v[206:209], v[188:191], v[6:9]
	v_mfma_f32_16x16x32_bf16 v[2:5], v[214:217], v[188:191], v[2:5]
	v_mfma_f32_16x16x32_bf16 v[46:49], v[206:209], v[160:163], v[46:49]
	v_mfma_f32_16x16x32_bf16 v[54:57], v[214:217], v[160:163], v[54:57]
	s_setprio 0
	s_add_i32 s42, 0, 0x18000
	v_add_u32_e32 v40, s42, v150
	s_barrier
	ds_read_b128 v[62:65], v40
	ds_read_b128 v[66:69], v40 offset:1024
	ds_read_b128 v[70:73], v40 offset:2048
	ds_read_b128 v[152:155], v40 offset:3072
	s_add_u32 s12, s12, 0x160000
	s_addc_u32 s13, s13, 0
	s_mov_b32 m0, s26
	v_lshl_add_u64 v[40:41], s[12:13], 0, v[0:1]
	ds_read_b128 v[156:159], v151 offset:32768
	ds_read_b128 v[160:163], v151 offset:33792
	ds_read_b128 v[164:167], v151 offset:34816
	ds_read_b128 v[168:171], v151 offset:35840
	ds_read_b128 v[172:175], v151 offset:36864
	ds_read_b128 v[176:179], v151 offset:37888
	ds_read_b128 v[184:187], v151 offset:38912
	ds_read_b128 v[188:191], v151 offset:39936
	global_load_lds_dwordx4 v[40:41], off
	v_lshl_add_u64 v[40:41], s[12:13], 0, v[34:35]
	s_mov_b32 m0, s27
	s_nop 0
	global_load_lds_dwordx4 v[40:41], off
	s_waitcnt lgkmcnt(8)
	s_barrier
	s_waitcnt lgkmcnt(0)
	s_setprio 1
	s_waitcnt lgkmcnt(0)
	v_mfma_f32_16x16x32_bf16 v[142:145], v[62:65], v[156:159], v[142:145]
	v_mfma_f32_16x16x32_bf16 v[138:141], v[70:73], v[156:159], v[138:141]
	v_mfma_f32_16x16x32_bf16 v[126:129], v[62:65], v[164:167], v[126:129]
	v_mfma_f32_16x16x32_bf16 v[122:125], v[70:73], v[164:167], v[122:125]
	v_mfma_f32_16x16x32_bf16 v[110:113], v[62:65], v[172:175], v[110:113]
	v_mfma_f32_16x16x32_bf16 v[106:109], v[70:73], v[172:175], v[106:109]
	v_mfma_f32_16x16x32_bf16 v[94:97], v[62:65], v[184:187], v[94:97]
	v_mfma_f32_16x16x32_bf16 v[90:93], v[70:73], v[184:187], v[90:93]
	v_mfma_f32_16x16x32_bf16 v[142:145], v[66:69], v[160:163], v[142:145]
	v_mfma_f32_16x16x32_bf16 v[138:141], v[152:155], v[160:163], v[138:141]
	v_mfma_f32_16x16x32_bf16 v[126:129], v[66:69], v[168:171], v[126:129]
	v_mfma_f32_16x16x32_bf16 v[122:125], v[152:155], v[168:171], v[122:125]
	v_mfma_f32_16x16x32_bf16 v[110:113], v[66:69], v[176:179], v[110:113]
	v_mfma_f32_16x16x32_bf16 v[106:109], v[152:155], v[176:179], v[106:109]
	v_mfma_f32_16x16x32_bf16 v[94:97], v[66:69], v[188:191], v[94:97]
	v_mfma_f32_16x16x32_bf16 v[90:93], v[152:155], v[188:191], v[90:93]
	s_setprio 0
	s_barrier
	s_add_i32 s12, 0, 0x1c000
	v_add_u32_e32 v40, s12, v150
	s_add_i32 s13, s42, s18
	ds_read_b128 v[202:205], v40
	ds_read_b128 v[206:209], v40 offset:1024
	ds_read_b128 v[210:213], v40 offset:2048
	ds_read_b128 v[214:217], v40 offset:3072
	v_lshl_add_u64 v[40:41], v[146:147], 0, s[90:91]
	s_mov_b32 m0, s13
	s_nop 0
	global_load_lds_dwordx4 v[40:41], off
	v_lshl_add_u64 v[40:41], v[180:181], 0, s[90:91]
	s_add_i32 m0, s13, 0x2000
	s_nop 0
	global_load_lds_dwordx4 v[40:41], off
	s_barrier
	s_waitcnt lgkmcnt(0)
	s_setprio 1
	s_waitcnt lgkmcnt(0)
	v_mfma_f32_16x16x32_bf16 v[134:137], v[202:205], v[156:159], v[134:137]
	v_mfma_f32_16x16x32_bf16 v[130:133], v[210:213], v[156:159], v[130:133]
	v_mfma_f32_16x16x32_bf16 v[118:121], v[202:205], v[164:167], v[118:121]
	v_mfma_f32_16x16x32_bf16 v[114:117], v[210:213], v[164:167], v[114:117]
	v_mfma_f32_16x16x32_bf16 v[102:105], v[202:205], v[172:175], v[102:105]
	v_mfma_f32_16x16x32_bf16 v[98:101], v[210:213], v[172:175], v[98:101]
	v_mfma_f32_16x16x32_bf16 v[86:89], v[202:205], v[184:187], v[86:89]
	v_mfma_f32_16x16x32_bf16 v[82:85], v[210:213], v[184:187], v[82:85]
	v_mfma_f32_16x16x32_bf16 v[134:137], v[206:209], v[160:163], v[134:137]
	v_mfma_f32_16x16x32_bf16 v[130:133], v[214:217], v[160:163], v[130:133]
	v_mfma_f32_16x16x32_bf16 v[118:121], v[206:209], v[168:171], v[118:121]
	v_mfma_f32_16x16x32_bf16 v[114:117], v[214:217], v[168:171], v[114:117]
	v_mfma_f32_16x16x32_bf16 v[102:105], v[206:209], v[176:179], v[102:105]
	v_mfma_f32_16x16x32_bf16 v[98:101], v[214:217], v[176:179], v[98:101]
	v_mfma_f32_16x16x32_bf16 v[86:89], v[206:209], v[188:191], v[86:89]
	v_mfma_f32_16x16x32_bf16 v[82:85], v[214:217], v[188:191], v[82:85]
	s_setprio 0
	s_mov_b32 m0, s31
	v_lshl_add_u64 v[40:41], v[182:183], 0, s[90:91]
	s_barrier
	ds_read_b128 v[156:159], v151 offset:49152
	ds_read_b128 v[160:163], v151 offset:50176
	ds_read_b128 v[164:167], v151 offset:51200
	ds_read_b128 v[168:171], v151 offset:52224
	ds_read_b128 v[172:175], v151 offset:53248
	ds_read_b128 v[176:179], v151 offset:54272
	ds_read_b128 v[184:187], v151 offset:55296
	ds_read_b128 v[188:191], v151 offset:56320
	global_load_lds_dwordx4 v[40:41], off
	v_lshl_add_u64 v[40:41], v[194:195], 0, s[90:91]
	s_mov_b32 m0, s34
	s_nop 0
	global_load_lds_dwordx4 v[40:41], off
	s_barrier
; #define PG8_STAGE(bufoff, gbase, voff) do { _Pragma("unroll") for (int _i = 0; _i < 2; ++_i) \
;         __builtin_amdgcn_global_load_lds((const unsigned*)((const char*)(gbase) + (voff)[_i]), (LAS unsigned*)(lds + (bufoff) + ldsw + _i * 8192), 16, 0, 0); } while (0)
; #define PG8_MMA(ai, bj, At, Bt) do { __builtin_amdgcn_s_setprio(1); _Pragma("unroll") for (int m = 0; m < 4; ++m) _Pragma("unroll") for (int n = 0; n < 2; ++n) _Pragma("unroll") for (int k = 0; k < 2; ++k) \
;         acc[ai][bj][m][n] = __builtin_amdgcn_mfma_f32_16x16x32_bf16(Bt[n][k], At[m][k], acc[ai][bj][m][n], 0, 0, 0); __builtin_amdgcn_s_setprio(0); } while (0)
; #define PG8_WAIT_V(n) asm volatile("s_waitcnt vmcnt(" #n ")" ::: "memory")
; #define PG8_WAIT_L(n) asm volatile("s_waitcnt lgkmcnt(" #n ")" ::: "memory")
; #define PG8_BAR __builtin_amdgcn_s_barrier()
; #define PG8_SCHED __builtin_amdgcn_sched_barrier(0)
; template <class Epi, class SchedT>
; DI void gemm_phase(LAS unsigned char* lds, const Gemm g, const SchedT& S, const Epi& E) {
;     ...
;             PG8_BAR; PG8_WAIT_L(0); PG8_MMA(1, 0, At, B0); PG8_BAR; PG8_SCHED;
;             PG8_STAGE(PG8_SB(1, 1), b3 + hstepB, voffB);
;             PG8_WAIT_V(6); PG8_BAR; PG8_MMA(1, 1, At, B1); PG8_BAR;
;         }
;         { int fr2 = fr, fq2 = fq, wr2 = wr, wc2 = wc; asm volatile("" : "+v"(fr2), "+v"(fq2), "+s"(wr2), "+s"(wc2));
;           E(acc, cur, wr2, wc2, fr2, fq2); }
;     ...
;     PG8_WAIT_V(0);
;     if (wr == 0) PG8_BAR;
;     PG8_BAR;
	s_waitcnt lgkmcnt(0)
	s_setprio 1
	s_waitcnt lgkmcnt(0)
	v_mfma_f32_16x16x32_bf16 v[78:81], v[62:65], v[156:159], v[78:81]
	v_mfma_f32_16x16x32_bf16 v[74:77], v[70:73], v[156:159], v[74:77]
	v_mfma_f32_16x16x32_bf16 v[58:61], v[62:65], v[164:167], v[58:61]
	v_mfma_f32_16x16x32_bf16 v[50:53], v[70:73], v[164:167], v[50:53]
	v_mfma_f32_16x16x32_bf16 v[30:33], v[62:65], v[172:175], v[30:33]
	v_mfma_f32_16x16x32_bf16 v[26:29], v[70:73], v[172:175], v[26:29]
	v_mfma_f32_16x16x32_bf16 v[14:17], v[62:65], v[184:187], v[14:17]
	v_mfma_f32_16x16x32_bf16 v[10:13], v[70:73], v[184:187], v[10:13]
	v_mfma_f32_16x16x32_bf16 v[78:81], v[66:69], v[160:163], v[78:81]
	v_mfma_f32_16x16x32_bf16 v[74:77], v[152:155], v[160:163], v[74:77]
	v_mfma_f32_16x16x32_bf16 v[58:61], v[66:69], v[168:171], v[58:61]
	v_mfma_f32_16x16x32_bf16 v[50:53], v[152:155], v[168:171], v[50:53]
	v_mfma_f32_16x16x32_bf16 v[30:33], v[66:69], v[176:179], v[30:33]
	v_mfma_f32_16x16x32_bf16 v[26:29], v[152:155], v[176:179], v[26:29]
	v_mfma_f32_16x16x32_bf16 v[14:17], v[66:69], v[188:191], v[14:17]
	v_mfma_f32_16x16x32_bf16 v[10:13], v[152:155], v[188:191], v[10:13]
	s_setprio 0
	s_barrier
	s_add_u32 s10, s10, 0x160080
	s_addc_u32 s11, s11, 0
	s_add_i32 s12, s12, s18
	v_lshl_add_u64 v[40:41], s[10:11], 0, v[0:1]
	s_mov_b32 m0, s12
	s_nop 0
	global_load_lds_dwordx4 v[40:41], off
	v_lshl_add_u64 v[40:41], s[10:11], 0, v[34:35]
	s_add_i32 m0, s12, 0x2000
	s_nop 0
	global_load_lds_dwordx4 v[40:41], off
	s_waitcnt vmcnt(6)
	s_barrier
	s_setprio 1
	v_mfma_f32_16x16x32_bf16 v[46:49], v[202:205], v[156:159], v[46:49]
	v_mfma_f32_16x16x32_bf16 v[70:73], v[206:209], v[160:163], v[46:49]
	v_mfma_f32_16x16x32_bf16 v[46:49], v[210:213], v[156:159], v[54:57]
	v_mfma_f32_16x16x32_bf16 v[40:43], v[202:205], v[164:167], v[42:45]
	v_mfma_f32_16x16x32_bf16 v[36:39], v[210:213], v[164:167], v[36:39]
	v_mfma_f32_16x16x32_bf16 v[22:25], v[202:205], v[172:175], v[22:25]
	v_mfma_f32_16x16x32_bf16 v[18:21], v[210:213], v[172:175], v[18:21]
	v_mfma_f32_16x16x32_bf16 v[6:9], v[202:205], v[184:187], v[6:9]
	v_mfma_f32_16x16x32_bf16 v[2:5], v[210:213], v[184:187], v[2:5]
	v_mfma_f32_16x16x32_bf16 v[66:69], v[214:217], v[160:163], v[46:49]
	v_mfma_f32_16x16x32_bf16 v[42:45], v[206:209], v[168:171], v[40:43]
	v_mfma_f32_16x16x32_bf16 v[38:41], v[214:217], v[168:171], v[36:39]
	v_mfma_f32_16x16x32_bf16 v[22:25], v[206:209], v[176:179], v[22:25]
	v_mfma_f32_16x16x32_bf16 v[18:21], v[214:217], v[176:179], v[18:21]
	v_mfma_f32_16x16x32_bf16 v[6:9], v[206:209], v[188:191], v[6:9]
	v_mfma_f32_16x16x32_bf16 v[2:5], v[214:217], v[188:191], v[2:5]
	s_setprio 0
	s_add_i32 s41, s41, 2
	s_add_u32 s8, s8, 0x100
	s_addc_u32 s9, s9, 0
	s_add_u32 s39, s39, 0x100
	s_addc_u32 s40, s40, 0
	s_cmpk_gt_u32 s41, 0x55
	s_barrier
	s_cbranch_scc0 .LBB0_1705
	s_cmp_eq_u32 s32, 0
	s_cbranch_scc1 .Lq_epi_normal
	s_cmp_eq_u32 s17, 0
	s_cbranch_scc0 .Lq_al0
	s_barrier
.Lq_al0:
	s_sub_u32 s12, s38, 64
	s_lshl_b32 s13, s33, 2
	s_add_u32 s12, s12, s13
	s_lshl_b32 s101, s12, 2
	s_sub_u32 s98, s32, 1
	s_add_u32 s13, s101, s98
	s_lshl_b32 s13, s13, 18
	s_add_u32 s8, s4, 0xcd01000
	s_addc_u32 s9, s5, 0
	s_add_u32 s8, s8, s13
	s_addc_u32 s9, s9, 0
	s_lshl_b32 s13, s12, 2
	s_sub_u32 s10, s4, 0x800
	s_subb_u32 s11, s5, 0
	s_add_u32 s10, s10, s13
	s_addc_u32 s11, s11, 0
	v_lshlrev_b32_e32 v202, 4, v192
	global_store_dwordx4 v202, v[2:5], s[8:9] sc0 sc1
	s_add_u32 s8, s8, 0x2000
	s_addc_u32 s9, s9, 0
	global_store_dwordx4 v202, v[6:9], s[8:9] sc0 sc1
	s_add_u32 s8, s8, 0x2000
	s_addc_u32 s9, s9, 0
	global_store_dwordx4 v202, v[10:13], s[8:9] sc0 sc1
	s_add_u32 s8, s8, 0x2000
	s_addc_u32 s9, s9, 0
	global_store_dwordx4 v202, v[14:17], s[8:9] sc0 sc1
	s_add_u32 s8, s8, 0x2000
	s_addc_u32 s9, s9, 0
	global_store_dwordx4 v202, v[18:21], s[8:9] sc0 sc1
	s_add_u32 s8, s8, 0x2000
	s_addc_u32 s9, s9, 0
	global_store_dwordx4 v202, v[22:25], s[8:9] sc0 sc1
	s_add_u32 s8, s8, 0x2000
	s_addc_u32 s9, s9, 0
	global_store_dwordx4 v202, v[26:29], s[8:9] sc0 sc1
	s_add_u32 s8, s8, 0x2000
	s_addc_u32 s9, s9, 0
	global_store_dwordx4 v202, v[30:33], s[8:9] sc0 sc1
	s_add_u32 s8, s8, 0x2000
	s_addc_u32 s9, s9, 0
	global_store_dwordx4 v202, v[38:41], s[8:9] sc0 sc1
	s_add_u32 s8, s8, 0x2000
	s_addc_u32 s9, s9, 0
	global_store_dwordx4 v202, v[42:45], s[8:9] sc0 sc1
	s_add_u32 s8, s8, 0x2000
	s_addc_u32 s9, s9, 0
	global_store_dwordx4 v202, v[50:53], s[8:9] sc0 sc1
	s_add_u32 s8, s8, 0x2000
	s_addc_u32 s9, s9, 0
	global_store_dwordx4 v202, v[58:61], s[8:9] sc0 sc1
	s_add_u32 s8, s8, 0x2000
	s_addc_u32 s9, s9, 0
	global_store_dwordx4 v202, v[66:69], s[8:9] sc0 sc1
	s_add_u32 s8, s8, 0x2000
	s_addc_u32 s9, s9, 0
	global_store_dwordx4 v202, v[70:73], s[8:9] sc0 sc1
	s_add_u32 s8, s8, 0x2000
	s_addc_u32 s9, s9, 0
	global_store_dwordx4 v202, v[74:77], s[8:9] sc0 sc1
	s_add_u32 s8, s8, 0x2000
	s_addc_u32 s9, s9, 0
	global_store_dwordx4 v202, v[78:81], s[8:9] sc0 sc1
	s_add_u32 s8, s8, 0x2000
	s_addc_u32 s9, s9, 0
	global_store_dwordx4 v202, v[82:85], s[8:9] sc0 sc1
	s_add_u32 s8, s8, 0x2000
	s_addc_u32 s9, s9, 0
	global_store_dwordx4 v202, v[86:89], s[8:9] sc0 sc1
	s_add_u32 s8, s8, 0x2000
	s_addc_u32 s9, s9, 0
	global_store_dwordx4 v202, v[90:93], s[8:9] sc0 sc1
	s_add_u32 s8, s8, 0x2000
	s_addc_u32 s9, s9, 0
	global_store_dwordx4 v202, v[94:97], s[8:9] sc0 sc1
	s_add_u32 s8, s8, 0x2000
	s_addc_u32 s9, s9, 0
	global_store_dwordx4 v202, v[98:101], s[8:9] sc0 sc1
	s_add_u32 s8, s8, 0x2000
	s_addc_u32 s9, s9, 0
	global_store_dwordx4 v202, v[102:105], s[8:9] sc0 sc1
	s_add_u32 s8, s8, 0x2000
	s_addc_u32 s9, s9, 0
	global_store_dwordx4 v202, v[106:109], s[8:9] sc0 sc1
	s_add_u32 s8, s8, 0x2000
	s_addc_u32 s9, s9, 0
	global_store_dwordx4 v202, v[110:113], s[8:9] sc0 sc1
	s_add_u32 s8, s8, 0x2000
	s_addc_u32 s9, s9, 0
	global_store_dwordx4 v202, v[114:117], s[8:9] sc0 sc1
	s_add_u32 s8, s8, 0x2000
	s_addc_u32 s9, s9, 0
	global_store_dwordx4 v202, v[118:121], s[8:9] sc0 sc1
	s_add_u32 s8, s8, 0x2000
	s_addc_u32 s9, s9, 0
	global_store_dwordx4 v202, v[122:125], s[8:9] sc0 sc1
	s_add_u32 s8, s8, 0x2000
	s_addc_u32 s9, s9, 0
	global_store_dwordx4 v202, v[126:129], s[8:9] sc0 sc1
	s_add_u32 s8, s8, 0x2000
	s_addc_u32 s9, s9, 0
	global_store_dwordx4 v202, v[130:133], s[8:9] sc0 sc1
	s_add_u32 s8, s8, 0x2000
	s_addc_u32 s9, s9, 0
	global_store_dwordx4 v202, v[134:137], s[8:9] sc0 sc1
	s_add_u32 s8, s8, 0x2000
	s_addc_u32 s9, s9, 0
	global_store_dwordx4 v202, v[138:141], s[8:9] sc0 sc1
	s_add_u32 s8, s8, 0x2000
	s_addc_u32 s9, s9, 0
	global_store_dwordx4 v202, v[142:145], s[8:9] sc0 sc1
	s_add_u32 s8, s8, 0x2000
	s_addc_u32 s9, s9, 0
	s_waitcnt vmcnt(0)
	s_barrier
	v_cmp_eq_u32_e32 vcc, 0, v192
	s_and_saveexec_b64 s[98:99], vcc
	s_cbranch_execz .Lq_t0done
	buffer_wbl2 sc1
	s_waitcnt vmcnt(0)
	v_mov_b32_e32 v203, 1
	v_mov_b32_e32 v204, 0
	global_atomic_add v203, v204, v203, s[10:11] sc0
	s_waitcnt vmcnt(0)
	buffer_inv sc1
	s_waitcnt vmcnt(0)
	v_mov_b32_e32 v204, 0x20400
	ds_write_b32 v204, v203
	s_waitcnt lgkmcnt(0)

; #define PG8_WAIT_V(n) asm volatile("s_waitcnt vmcnt(" #n ")" ::: "memory")
; #define PG8_BAR __builtin_amdgcn_s_barrier()
; template <class Epi, class SchedT>
; DI void gemm_phase(LAS unsigned char* lds, const Gemm g, const SchedT& S, const Epi& E) {
;     ...
;     PG8_WAIT_V(0);
;     if (wr == 0) PG8_BAR;
;     PG8_BAR;
.Lq_epi_end:
	s_cmp_eq_u32 s32, 0
	s_cbranch_scc1 .Lq_al1
	s_cmp_eq_u32 s17, 1
	s_cbranch_scc0 .Lq_al1
	s_barrier
